# remaining literal-zero v_mov_b32 runs (attention S/O accumulators, SGU) paired into v_mov_b64
# baseline (speedup 1.0000x reference)
; __device__ __forceinline__ void phase_attn_items(const Params& P, LAS unsigned char* lds) {
;     ...
;         if (xmap) { const int g = it * 32 + (blockIdx.x >> 3), pair = 4 * (blockIdx.x & 7) + g / 48, within = g % 48; pat = within >> 4; rc = within & 15; b = pair >> 3; hh = pair & 7; }
;         else { const int item = it * gridDim.x + blockIdx.x; if (item >= 3 * 512) break; pat = item >> 9; const int rem = item & 511; b = rem >> 7; hh = (rem >> 4) & 7; rc = rem & 15; }
;         const int dlog = 2 * pat, r = pat == 0 ? 0 : (pat == 1 ? rc >> 2 : rc), ch8 = pat == 0 ? rc : (pat == 1 ? rc & 3 : 0);
;         const int ntile = (SEQ >> dlog) >> 5, ql = lane & 31, h = lane >> 5;
;         const size_t rowbase = (size_t)b * SEQ;
;         const size_t hb = (size_t)hh * 256;
;     ...
;         const int trow = (tid >> 4) & 31, tch = tid & 15;
;         const unsigned roff = (unsigned)((trow << dlog) * AW + tch * 8) * 2u;
;         const unsigned loff = off_b(trow, tch);
;         u32x4 kk[12];
; #pragma unroll
;         for (int i = 0; i < 12; ++i) { const int T = 8 * ch8 - 2 + i; if (T >= 0 && T < ntile) kk[i] = *(const u32x4*)(TILE_BASE(Kb, T) + roff); else kk[i] = (u32x4){0u, 0u, 0u, 0u}; }
.LBB0_125:
	s_andn2_b64 vcc, exec, s[24:25]
	s_cbranch_vccnz .LBB0_114
	s_lshl_b32 s98, s26, 1
	s_ashr_i32 s2, s9, 2
	s_and_b32 s3, s9, 3
	s_cmp_eq_u32 s26, 1
	s_cselect_b32 s2, s2, s9
	s_cselect_b32 s3, s3, 0
	s_cmp_eq_u32 s26, 0
	s_cselect_b32 s30, 0, s2
	s_cselect_b32 s99, s9, s3
	s_ashr_i32 s13, s12, 31
	s_lshl_b64 s[2:3], s[12:13], 12
	s_ashr_i32 s17, s16, 31
	s_lshl_b32 s13, s99, 3
	s_ashr_i32 s33, s30, 31
	s_lshr_b32 s27, 0x80, s98
	s_lshl_b64 s[44:45], s[16:17], 8
	s_add_i32 s20, s13, -2
	v_readlane_b32 s5, v247, 5
	s_add_u32 s24, s5, s44
	v_readlane_b32 s5, v247, 6
	s_addc_u32 s25, s5, s45
	s_add_u32 s42, s2, s30
	s_addc_u32 s43, s3, s33
	v_lshlrev_b32_e32 v0, s98, v167
	s_cmp_gt_i32 s99, 0
	v_lshl_or_b32 v0, v0, 11, v168
	s_cselect_b64 s[2:3], -1, 0
	s_cmp_le_i32 s13, s27
	v_lshl_add_u64 v[50:51], s[24:25], 0, v[0:1]
	s_cselect_b64 s[24:25], -1, 0
	s_and_b64 s[2:3], s[2:3], s[24:25]
	v_cndmask_b32_e64 v3, 0, 1, s[2:3]
	s_mov_b32 s4, s90
	v_mov_b32_e32 v2, 0
	v_cmp_ne_u32_e64 s[40:41], 1, v3
	s_andn2_b64 vcc, exec, s[2:3]
	v_mov_b64_e32 v[6:7], 0
	v_mov_b64_e32 v[8:9], 0
	s_cbranch_vccnz .LBB0_128
	s_lshl_b32 s30, s20, 5
	s_lshl_b64 s[2:3], s[30:31], s98
	s_add_u32 s2, s2, s42
	s_addc_u32 s3, s3, s43
	s_lshl_b64 s[2:3], s[2:3], 11
	v_lshl_add_u64 v[4:5], v[50:51], 0, s[2:3]
	global_load_dwordx4 v[6:9], v[4:5], off
.LBB0_128:
	s_mov_b32 s59, s91
	s_mov_b32 s58, s78
	s_add_i32 s90, s13, -1
	s_and_b64 vcc, exec, s[40:41]
	v_mov_b64_e32 v[10:11], 0
	v_mov_b64_e32 v[12:13], 0
	s_cbranch_vccnz .LBB0_130
	s_lshl_b32 s30, s90, 5
	s_lshl_b64 s[2:3], s[30:31], s98
	s_add_u32 s2, s2, s42
	s_addc_u32 s3, s3, s43
	s_lshl_b64 s[2:3], s[2:3], 11
	v_lshl_add_u64 v[4:5], v[50:51], 0, s[2:3]
	global_load_dwordx4 v[10:13], v[4:5], off

; __device__ __forceinline__ void phase_attn_items(const Params& P, LAS unsigned char* lds) {
;     ...
;         for (int i = 0; i < 12; ++i) { const int T = 8 * ch8 - 2 + i; if (T >= 0 && T < ntile) kk[i] = *(const u32x4*)(TILE_BASE(Kb, T) + roff); else kk[i] = (u32x4){0u, 0u, 0u, 0u}; }
.LBB0_132:
	s_or_b32 s3, s13, 1
	s_cmp_lt_i32 s3, s27
	s_mov_b64 s[36:37], s[88:89]
	v_mov_b32_e32 v14, 0
	s_cselect_b64 s[48:49], -1, 0
	s_cmp_ge_i32 s3, s27
	v_mov_b64_e32 v[18:19], 0
	v_mov_b64_e32 v[20:21], 0
	s_cbranch_scc1 .LBB0_134
	s_lshl_b32 s30, s3, 5
	s_lshl_b64 s[24:25], s[30:31], s98
	s_add_u32 s24, s24, s42
	s_addc_u32 s25, s25, s43
	s_lshl_b64 s[24:25], s[24:25], 11
	v_lshl_add_u64 v[16:17], v[50:51], 0, s[24:25]
	global_load_dwordx4 v[18:21], v[16:17], off

; __device__ __forceinline__ void phase_attn_items(const Params& P, LAS unsigned char* lds) {
;     ...
;         for (int i = 0; i < 12; ++i) { const int T = 8 * ch8 - 2 + i; if (T >= 0 && T < ntile) kk[i] = *(const u32x4*)(TILE_BASE(Kb, T) + roff); else kk[i] = (u32x4){0u, 0u, 0u, 0u}; }
.LBB0_136:
	s_or_b32 s33, s13, 3
	s_cmp_lt_i32 s33, s27
	s_mov_b64 s[68:69], s[96:97]
	v_mov_b32_e32 v22, 0
	s_cselect_b64 s[52:53], -1, 0
	s_cmp_ge_i32 s33, s27
	v_mov_b64_e32 v[26:27], 0
	v_mov_b64_e32 v[28:29], 0
	s_cbranch_scc1 .LBB0_138
	s_lshl_b32 s30, s33, 5
	s_lshl_b64 s[24:25], s[30:31], s98
	s_add_u32 s24, s24, s42
	s_addc_u32 s25, s25, s43
	s_lshl_b64 s[24:25], s[24:25], 11
	v_lshl_add_u64 v[24:25], v[50:51], 0, s[24:25]
	global_load_dwordx4 v[26:29], v[24:25], off

; __device__ __forceinline__ void phase_attn_items(const Params& P, LAS unsigned char* lds) {
;     ...
;         for (int i = 0; i < 12; ++i) { const int T = 8 * ch8 - 2 + i; if (T >= 0 && T < ntile) kk[i] = *(const u32x4*)(TILE_BASE(Kb, T) + roff); else kk[i] = (u32x4){0u, 0u, 0u, 0u}; }
.LBB0_140:
	s_or_b32 s92, s13, 5
	s_cmp_lt_i32 s92, s27
	v_mov_b32_e32 v30, 0
	s_cselect_b64 s[56:57], -1, 0
	s_cmp_ge_i32 s92, s27
	v_mov_b64_e32 v[34:35], 0
	v_mov_b64_e32 v[36:37], 0
	s_cbranch_scc1 .LBB0_142
	s_lshl_b32 s30, s92, 5
	s_lshl_b64 s[24:25], s[30:31], s98
	s_add_u32 s24, s24, s42
	s_addc_u32 s25, s25, s43
	s_lshl_b64 s[24:25], s[24:25], 11
	v_lshl_add_u64 v[32:33], v[50:51], 0, s[24:25]
	global_load_dwordx4 v[34:37], v[32:33], off

; __device__ __forceinline__ void phase_attn_items(const Params& P, LAS unsigned char* lds) {
;     ...
;         for (int i = 0; i < 12; ++i) { const int T = 8 * ch8 - 2 + i; if (T >= 0 && T < ntile) kk[i] = *(const u32x4*)(TILE_BASE(Kb, T) + roff); else kk[i] = (u32x4){0u, 0u, 0u, 0u}; }
.LBB0_144:
	s_or_b32 s93, s13, 7
	s_cmp_lt_i32 s93, s27
	s_mov_b32 s5, s94
	v_mov_b32_e32 v38, 0
	s_cselect_b64 s[24:25], -1, 0
	s_cmp_ge_i32 s93, s27
	v_mov_b64_e32 v[42:43], 0
	v_mov_b64_e32 v[44:45], 0
	s_cbranch_scc1 .LBB0_146
	s_lshl_b32 s30, s93, 5
	s_lshl_b64 s[64:65], s[30:31], s98
	s_add_u32 s64, s64, s42
	s_addc_u32 s65, s65, s43
	s_lshl_b64 s[64:65], s[64:65], 11
	v_lshl_add_u64 v[40:41], v[50:51], 0, s[64:65]
	global_load_dwordx4 v[42:45], v[40:41], off

; __device__ __forceinline__ void phase_attn_items(const Params& P, LAS unsigned char* lds) {
;     ...
;         for (int i = 0; i < 12; ++i) { const int T = 8 * ch8 - 2 + i; if (T >= 0 && T < ntile) kk[i] = *(const u32x4*)(TILE_BASE(Kb, T) + roff); else kk[i] = (u32x4){0u, 0u, 0u, 0u}; }
.LBB0_148:
	s_add_i32 s95, s13, 9
	s_cmp_lt_i32 s95, s27
	v_mov_b32_e32 v82, 0
	s_cselect_b64 s[66:67], -1, 0
	s_cmp_ge_i32 s95, s27
	v_mov_b64_e32 v[46:47], 0
	v_mov_b64_e32 v[48:49], 0
	s_cbranch_scc1 .LBB0_150
	s_lshl_b32 s30, s95, 5
	s_lshl_b64 s[72:73], s[30:31], s98
	s_add_u32 s72, s72, s42
	s_addc_u32 s73, s73, s43
	s_lshl_b64 s[72:73], s[72:73], 11
	v_lshl_add_u64 v[46:47], v[50:51], 0, s[72:73]
	global_load_dwordx4 v[46:49], v[46:47], off

; __device__ __forceinline__ void phase_attn_items(const Params& P, LAS unsigned char* lds) {
;     ...
;         for (int i = 0; i < 12; ++i) { const int T = 8 * ch8 - 2 + i; if (T >= 0 && T < ntile) vv[i] = *(const u32x4*)(TILE_BASE(Vb, T) + roff); else vv[i] = (u32x4){0u, 0u, 0u, 0u}; }
.LBB0_152:
	v_mov_b32_e32 v86, 0
	s_and_b64 vcc, exec, s[40:41]
	v_mov_b64_e32 v[90:91], 0
	v_mov_b64_e32 v[92:93], 0
	s_cbranch_vccnz .LBB0_154
	s_lshl_b32 s30, s90, 5
	s_lshl_b64 s[40:41], s[30:31], s98
	s_add_u32 s40, s40, s42
	s_addc_u32 s41, s41, s43
	s_lshl_b64 s[40:41], s[40:41], 11
	v_lshl_add_u64 v[2:3], v[4:5], 0, s[40:41]
	global_load_dwordx4 v[90:93], v[2:3], off

; __device__ __forceinline__ void phase_attn_items(const Params& P, LAS unsigned char* lds) {
;     ...
;         for (int i = 0; i < 12; ++i) { const int T = 8 * ch8 - 2 + i; if (T >= 0 && T < ntile) vv[i] = *(const u32x4*)(TILE_BASE(Vb, T) + roff); else vv[i] = (u32x4){0u, 0u, 0u, 0u}; }
.LBB0_156:
	v_mov_b32_e32 v94, 0
	s_andn2_b64 vcc, exec, s[48:49]
	v_mov_b64_e32 v[98:99], 0
	v_mov_b64_e32 v[100:101], 0
	s_mov_b32 s90, s4
	s_cbranch_vccnz .LBB0_158
	s_lshl_b32 s30, s3, 5
	s_lshl_b64 s[40:41], s[30:31], s98
	s_add_u32 s40, s40, s42
	s_addc_u32 s41, s41, s43
	s_lshl_b64 s[40:41], s[40:41], 11
	v_lshl_add_u64 v[2:3], v[4:5], 0, s[40:41]
	global_load_dwordx4 v[98:101], v[2:3], off

; __device__ __forceinline__ void phase_attn_items(const Params& P, LAS unsigned char* lds) {
;     ...
;         for (int i = 0; i < 12; ++i) { const int T = 8 * ch8 - 2 + i; if (T >= 0 && T < ntile) vv[i] = *(const u32x4*)(TILE_BASE(Vb, T) + roff); else vv[i] = (u32x4){0u, 0u, 0u, 0u}; }
.LBB0_160:
	v_mov_b32_e32 v102, 0
	s_andn2_b64 vcc, exec, s[52:53]
	v_mov_b64_e32 v[106:107], 0
	v_mov_b64_e32 v[108:109], 0
	s_cbranch_vccnz .LBB0_162
	s_lshl_b32 s30, s33, 5
	s_lshl_b64 s[40:41], s[30:31], s98
	s_add_u32 s40, s40, s42
	s_addc_u32 s41, s41, s43
	s_lshl_b64 s[40:41], s[40:41], 11
	v_lshl_add_u64 v[2:3], v[4:5], 0, s[40:41]
	global_load_dwordx4 v[106:109], v[2:3], off

; __device__ __forceinline__ void phase_attn_items(const Params& P, LAS unsigned char* lds) {
;     ...
;         for (int i = 0; i < 12; ++i) { const int T = 8 * ch8 - 2 + i; if (T >= 0 && T < ntile) vv[i] = *(const u32x4*)(TILE_BASE(Vb, T) + roff); else vv[i] = (u32x4){0u, 0u, 0u, 0u}; }
.LBB0_164:
	v_mov_b32_e32 v110, 0
	s_andn2_b64 vcc, exec, s[56:57]
	v_mov_b64_e32 v[114:115], 0
	v_mov_b64_e32 v[116:117], 0
	s_cbranch_vccnz .LBB0_166
	s_lshl_b32 s30, s92, 5
	s_lshl_b64 s[40:41], s[30:31], s98
	s_add_u32 s40, s40, s42
	s_addc_u32 s41, s41, s43
	s_lshl_b64 s[40:41], s[40:41], 11
	v_lshl_add_u64 v[2:3], v[4:5], 0, s[40:41]
	global_load_dwordx4 v[114:117], v[2:3], off

; __device__ __forceinline__ void phase_attn_items(const Params& P, LAS unsigned char* lds) {
;     ...
;         for (int i = 0; i < 12; ++i) { const int T = 8 * ch8 - 2 + i; if (T >= 0 && T < ntile) vv[i] = *(const u32x4*)(TILE_BASE(Vb, T) + roff); else vv[i] = (u32x4){0u, 0u, 0u, 0u}; }
.LBB0_168:
	v_mov_b32_e32 v118, 0
	s_andn2_b64 vcc, exec, s[24:25]
	v_mov_b64_e32 v[122:123], 0
	v_mov_b64_e32 v[124:125], 0
	s_cbranch_vccnz .LBB0_170
	s_lshl_b32 s30, s93, 5
	s_lshl_b64 s[2:3], s[30:31], s98
	s_add_u32 s2, s2, s42
	s_addc_u32 s3, s3, s43
	s_lshl_b64 s[2:3], s[2:3], 11
	v_lshl_add_u64 v[2:3], v[4:5], 0, s[2:3]
	global_load_dwordx4 v[122:125], v[2:3], off

; #define LAS __attribute__((address_space(3)))
; #define MFMA32(a, b, c) __builtin_amdgcn_mfma_f32_32x32x16_bf16((a), (b), (c), 0, 0, 0)
; __device__ __forceinline__ void phase_attn_items(const Params& P, LAS unsigned char* lds) {
;     ...
;         for (int i = 0; i < 12; ++i) { const int T = 8 * ch8 - 2 + i; if (T >= 0 && T < ntile) vv[i] = *(const u32x4*)(TILE_BASE(Vb, T) + roff); else vv[i] = (u32x4){0u, 0u, 0u, 0u}; }
;         __syncthreads();
;         f32x16 S[5];
; #pragma unroll
;         for (int kt = 0; kt < 5; ++kt) {
;             const int T = qt + kt - 2; const bool tv = (T >= 0) && (T < ntile);
;             f32x16 s;
; #pragma unroll
;             for (int i = 0; i < 16; ++i) s[i] = 0.f;
;             if (tv) {
;                 const LAS unsigned char* kl = lds + (wave + kt) * 8192;
;                 bf16x8 kf[8];
; #pragma unroll
;                 for (int ks = 0; ks < 8; ++ks) kf[ks] = *(const LAS bf16x8*)(kl + off_b(ql, 2 * ks + h));
; #pragma unroll
;                 for (int ks = 0; ks < 8; ++ks) s = MFMA32(kf[ks], qf[ks], s);
;             }
;             S[kt] = s;
.LBB0_172:
	v_mov_b32_e32 v2, 0
	s_andn2_b64 vcc, exec, s[66:67]
	v_mov_b64_e32 v[126:127], 0
	v_mov_b64_e32 v[128:129], 0
	s_mov_b64 s[92:93], s[96:97]
	s_cbranch_vccnz .LBB0_174
	s_lshl_b32 s30, s95, 5
	s_lshl_b64 s[2:3], s[30:31], s98
	s_add_u32 s2, s2, s42
	s_addc_u32 s3, s3, s43
	s_lshl_b64 s[2:3], s[2:3], 11
	v_lshl_add_u64 v[4:5], v[4:5], 0, s[2:3]
	global_load_dwordx4 v[126:129], v[4:5], off
.LBB0_174:
	s_add_i32 s2, s27, 2
	s_cmp_lt_i32 s13, s2
	s_cselect_b64 s[2:3], -1, 0
	s_cmp_gt_i32 s13, 1
	s_cselect_b64 s[24:25], -1, 0
	v_lshlrev_b32_e32 v3, 2, v165
	v_bfe_u32 v0, v174, 2, 2
	s_and_b64 s[50:51], s[24:25], s[2:3]
	v_and_or_b32 v3, v3, 12, v0
	v_lshl_add_u32 v4, v165, 8, 0
	v_cndmask_b32_e64 v5, 0, 1, s[50:51]
	v_readlane_b32 s2, v247, 14
	v_cmp_ne_u32_e64 s[40:41], 1, v5
	v_add_u32_e32 v5, 2, v164
	v_add_u32_e32 v175, s2, v4
	v_xor_b32_e32 v4, v3, v164
	v_add_u32_e32 v6, 4, v164
	v_add_u32_e32 v7, 6, v164
	v_add_u32_e32 v8, 8, v164
	v_add_u32_e32 v9, 10, v164
	v_add_u32_e32 v10, 12, v164
	v_add_u32_e32 v11, 14, v164
	s_andn2_b64 vcc, exec, s[50:51]
	v_lshl_add_u32 v189, v4, 4, v175
	v_xor_b32_e32 v190, v3, v5
	v_xor_b32_e32 v188, v3, v6
	v_xor_b32_e32 v187, v3, v7
	v_xor_b32_e32 v186, v3, v8
	v_xor_b32_e32 v185, v3, v9
	v_xor_b32_e32 v177, v3, v10
	v_xor_b32_e32 v176, v3, v11
	v_mov_b32_e32 v3, 0
	v_mov_b64_e32 v[4:5], 0
	v_mov_b64_e32 v[6:7], 0
	v_mov_b64_e32 v[8:9], 0
	v_mov_b64_e32 v[10:11], 0
	v_mov_b64_e32 v[12:13], 0
	v_mov_b64_e32 v[14:15], 0
	v_mov_b64_e32 v[16:17], 0
	s_mov_b32 s94, s5
	s_mov_b64 s[96:97], s[68:69]
	s_waitcnt lgkmcnt(0)
	s_barrier
	s_cbranch_vccnz .LBB0_176
	ds_read_b128 v[208:211], v189
	v_lshl_add_u32 v240, v190, 4, v175
	ds_read_b128 v[212:215], v240
	v_lshl_add_u32 v240, v188, 4, v175
	ds_read_b128 v[216:219], v240
	v_lshl_add_u32 v240, v187, 4, v175
	ds_read_b128 v[220:223], v240
	v_lshl_add_u32 v240, v186, 4, v175
	ds_read_b128 v[224:227], v240
	v_lshl_add_u32 v240, v185, 4, v175
	ds_read_b128 v[228:231], v240
	v_lshl_add_u32 v240, v177, 4, v175
	ds_read_b128 v[232:235], v240
	v_lshl_add_u32 v240, v176, 4, v175
	ds_read_b128 v[236:239], v240
	s_waitcnt lgkmcnt(7)
	v_mfma_f32_32x32x16_bf16 v[2:17], v[208:211], v[158:161], 0
	s_waitcnt lgkmcnt(6)
	v_mfma_f32_32x32x16_bf16 v[2:17], v[212:215], v[154:157], v[2:17]
	s_waitcnt lgkmcnt(5)
	v_mfma_f32_32x32x16_bf16 v[2:17], v[216:219], v[150:153], v[2:17]
	s_waitcnt lgkmcnt(4)
	v_mfma_f32_32x32x16_bf16 v[2:17], v[220:223], v[146:149], v[2:17]
	s_waitcnt lgkmcnt(3)
	v_mfma_f32_32x32x16_bf16 v[2:17], v[224:227], v[142:145], v[2:17]
	s_waitcnt lgkmcnt(2)
	v_mfma_f32_32x32x16_bf16 v[2:17], v[228:231], v[138:141], v[2:17]
	s_waitcnt lgkmcnt(1)
	v_mfma_f32_32x32x16_bf16 v[2:17], v[232:235], v[134:137], v[2:17]
	s_waitcnt lgkmcnt(0)
	v_mfma_f32_32x32x16_bf16 v[2:17], v[236:239], v[130:133], v[2:17]
.LBB0_176:
	s_cmp_le_i32 s13, s27
	s_cselect_b64 s[2:3], -1, 0
	s_cmp_gt_i32 s13, 0
	s_cselect_b64 s[24:25], -1, 0
	s_and_b64 s[52:53], s[24:25], s[2:3]
	v_cndmask_b32_e64 v19, 0, 1, s[52:53]
	v_mov_b32_e32 v18, 0
	v_cmp_ne_u32_e64 s[42:43], 1, v19
	s_andn2_b64 vcc, exec, s[52:53]
	v_mov_b64_e32 v[34:35], 0
	v_mov_b64_e32 v[36:37], 0
	v_mov_b64_e32 v[38:39], 0
	v_mov_b64_e32 v[40:41], 0
	v_mov_b64_e32 v[42:43], 0
	v_mov_b64_e32 v[44:45], 0
	v_mov_b64_e32 v[46:47], 0
	v_mov_b64_e32 v[48:49], 0
	s_mov_b64 s[68:69], s[86:87]
	s_mov_b32 s95, s88
	s_cbranch_vccnz .LBB0_178
	ds_read_b128 v[208:211], v189 offset:8192
	v_lshl_add_u32 v240, v190, 4, v175
	ds_read_b128 v[212:215], v240 offset:8192
	v_lshl_add_u32 v240, v188, 4, v175
	ds_read_b128 v[216:219], v240 offset:8192
	v_lshl_add_u32 v240, v187, 4, v175
	ds_read_b128 v[220:223], v240 offset:8192
	v_lshl_add_u32 v240, v186, 4, v175
	ds_read_b128 v[224:227], v240 offset:8192
	v_lshl_add_u32 v240, v185, 4, v175
	ds_read_b128 v[228:231], v240 offset:8192
	v_lshl_add_u32 v240, v177, 4, v175
	ds_read_b128 v[232:235], v240 offset:8192
	v_lshl_add_u32 v240, v176, 4, v175
	ds_read_b128 v[236:239], v240 offset:8192
	s_waitcnt lgkmcnt(7)
	v_mfma_f32_32x32x16_bf16 v[34:49], v[208:211], v[158:161], 0
	s_waitcnt lgkmcnt(6)
	v_mfma_f32_32x32x16_bf16 v[34:49], v[212:215], v[154:157], v[34:49]
	s_waitcnt lgkmcnt(5)
	v_mfma_f32_32x32x16_bf16 v[34:49], v[216:219], v[150:153], v[34:49]
	s_waitcnt lgkmcnt(4)
	v_mfma_f32_32x32x16_bf16 v[34:49], v[220:223], v[146:149], v[34:49]
	s_waitcnt lgkmcnt(3)
	v_mfma_f32_32x32x16_bf16 v[34:49], v[224:227], v[142:145], v[34:49]
	s_waitcnt lgkmcnt(2)
	v_mfma_f32_32x32x16_bf16 v[34:49], v[228:231], v[138:141], v[34:49]
	s_waitcnt lgkmcnt(1)
	v_mfma_f32_32x32x16_bf16 v[34:49], v[232:235], v[134:137], v[34:49]
	s_waitcnt lgkmcnt(0)
	v_mfma_f32_32x32x16_bf16 v[34:49], v[236:239], v[130:133], v[34:49]
; #define LAS __attribute__((address_space(3)))
; #define MFMA32(a, b, c) __builtin_amdgcn_mfma_f32_32x32x16_bf16((a), (b), (c), 0, 0, 0)
; __device__ __forceinline__ void phase_attn_items(const Params& P, LAS unsigned char* lds) {
;     ...
;         for (int kt = 0; kt < 5; ++kt) {
;             const int T = qt + kt - 2; const bool tv = (T >= 0) && (T < ntile);
;             f32x16 s;
; #pragma unroll
;             for (int i = 0; i < 16; ++i) s[i] = 0.f;
;             if (tv) {
;                 const LAS unsigned char* kl = lds + (wave + kt) * 8192;
;                 bf16x8 kf[8];
; #pragma unroll
;                 for (int ks = 0; ks < 8; ++ks) kf[ks] = *(const LAS bf16x8*)(kl + off_b(ql, 2 * ks + h));
; #pragma unroll
;                 for (int ks = 0; ks < 8; ++ks) s = MFMA32(kf[ks], qf[ks], s);
;             }
;             S[kt] = s;
.LBB0_178:
	s_cmp_lt_i32 s13, s27
	s_cselect_b64 s[2:3], -1, 0
	s_cmp_gt_i32 s13, -1
	s_cselect_b64 s[24:25], -1, 0
	s_and_b64 s[54:55], s[24:25], s[2:3]
	v_cndmask_b32_e64 v19, 0, 1, s[54:55]
	v_readlane_b32 s86, v252, 38
	v_cmp_ne_u32_e64 s[44:45], 1, v19
	s_andn2_b64 vcc, exec, s[54:55]
	v_mov_b32_e32 v19, 0
	v_mov_b64_e32 v[20:21], 0
	v_mov_b64_e32 v[22:23], 0
	v_mov_b64_e32 v[24:25], 0
	v_mov_b64_e32 v[26:27], 0
	v_mov_b64_e32 v[28:29], 0
	v_mov_b64_e32 v[30:31], 0
	v_mov_b64_e32 v[32:33], 0
	v_readlane_b32 s87, v252, 39
	s_mov_b64 s[88:89], s[36:37]
	s_cbranch_vccnz .LBB0_180
	ds_read_b128 v[208:211], v189 offset:16384
	v_lshl_add_u32 v240, v190, 4, v175
	ds_read_b128 v[212:215], v240 offset:16384
	v_lshl_add_u32 v240, v188, 4, v175
	ds_read_b128 v[216:219], v240 offset:16384
	v_lshl_add_u32 v240, v187, 4, v175
	ds_read_b128 v[220:223], v240 offset:16384
	v_lshl_add_u32 v240, v186, 4, v175
	ds_read_b128 v[224:227], v240 offset:16384
	v_lshl_add_u32 v240, v185, 4, v175
	ds_read_b128 v[228:231], v240 offset:16384
	v_lshl_add_u32 v240, v177, 4, v175
	ds_read_b128 v[232:235], v240 offset:16384
	v_lshl_add_u32 v240, v176, 4, v175
	ds_read_b128 v[236:239], v240 offset:16384
	s_waitcnt lgkmcnt(7)
	v_mfma_f32_32x32x16_bf16 v[18:33], v[208:211], v[158:161], 0
	s_waitcnt lgkmcnt(6)
	v_mfma_f32_32x32x16_bf16 v[18:33], v[212:215], v[154:157], v[18:33]
	s_waitcnt lgkmcnt(5)
	v_mfma_f32_32x32x16_bf16 v[18:33], v[216:219], v[150:153], v[18:33]
	s_waitcnt lgkmcnt(4)
	v_mfma_f32_32x32x16_bf16 v[18:33], v[220:223], v[146:149], v[18:33]
	s_waitcnt lgkmcnt(3)
	v_mfma_f32_32x32x16_bf16 v[18:33], v[224:227], v[142:145], v[18:33]
	s_waitcnt lgkmcnt(2)
	v_mfma_f32_32x32x16_bf16 v[18:33], v[228:231], v[138:141], v[18:33]
	s_waitcnt lgkmcnt(1)
	v_mfma_f32_32x32x16_bf16 v[18:33], v[232:235], v[134:137], v[18:33]
	s_waitcnt lgkmcnt(0)
	v_mfma_f32_32x32x16_bf16 v[18:33], v[236:239], v[130:133], v[18:33]
.LBB0_180:
	s_add_i32 s2, s13, 1
	s_cmp_lt_i32 s2, s27
	s_cselect_b64 s[2:3], -1, 0
	s_cmp_gt_i32 s13, -2
	s_cselect_b64 s[24:25], -1, 0
	s_and_b64 s[56:57], s[24:25], s[2:3]
	v_cndmask_b32_e64 v51, 0, 1, s[56:57]
	v_mov_b32_e32 v50, 0
	v_cmp_ne_u32_e64 s[46:47], 1, v51
	s_andn2_b64 vcc, exec, s[56:57]
	v_mov_b64_e32 v[66:67], 0
	v_mov_b64_e32 v[68:69], 0
	v_mov_b64_e32 v[70:71], 0
	v_mov_b64_e32 v[72:73], 0
	v_mov_b64_e32 v[74:75], 0
	v_mov_b64_e32 v[76:77], 0
	v_mov_b64_e32 v[78:79], 0
	v_mov_b64_e32 v[80:81], 0
	s_mov_b32 s36, s91
	s_mov_b32 s37, s78
	s_cbranch_vccnz .LBB0_182
	ds_read_b128 v[208:211], v189 offset:24576
	v_lshl_add_u32 v240, v190, 4, v175
	ds_read_b128 v[212:215], v240 offset:24576
	v_lshl_add_u32 v240, v188, 4, v175
	ds_read_b128 v[216:219], v240 offset:24576
	v_lshl_add_u32 v240, v187, 4, v175
	ds_read_b128 v[220:223], v240 offset:24576
	v_lshl_add_u32 v240, v186, 4, v175
	ds_read_b128 v[224:227], v240 offset:24576
	v_lshl_add_u32 v240, v185, 4, v175
	ds_read_b128 v[228:231], v240 offset:24576
	v_lshl_add_u32 v240, v177, 4, v175
	ds_read_b128 v[232:235], v240 offset:24576
	v_lshl_add_u32 v240, v176, 4, v175
	ds_read_b128 v[236:239], v240 offset:24576
	s_waitcnt lgkmcnt(7)
	v_mfma_f32_32x32x16_bf16 v[66:81], v[208:211], v[158:161], 0
	s_waitcnt lgkmcnt(6)
	v_mfma_f32_32x32x16_bf16 v[66:81], v[212:215], v[154:157], v[66:81]
	s_waitcnt lgkmcnt(5)
	v_mfma_f32_32x32x16_bf16 v[66:81], v[216:219], v[150:153], v[66:81]
	s_waitcnt lgkmcnt(4)
	v_mfma_f32_32x32x16_bf16 v[66:81], v[220:223], v[146:149], v[66:81]
	s_waitcnt lgkmcnt(3)
	v_mfma_f32_32x32x16_bf16 v[66:81], v[224:227], v[142:145], v[66:81]
	s_waitcnt lgkmcnt(2)
	v_mfma_f32_32x32x16_bf16 v[66:81], v[228:231], v[138:141], v[66:81]
	s_waitcnt lgkmcnt(1)
	v_mfma_f32_32x32x16_bf16 v[66:81], v[232:235], v[134:137], v[66:81]
	s_waitcnt lgkmcnt(0)
	v_mfma_f32_32x32x16_bf16 v[66:81], v[236:239], v[130:133], v[66:81]
.LBB0_182:
	s_add_i32 s2, s13, 2
	s_cmp_lt_i32 s2, s27
	s_cselect_b64 s[2:3], -1, 0
	s_cmp_gt_i32 s13, -3
	s_cselect_b64 s[24:25], -1, 0
	s_and_b64 s[24:25], s[24:25], s[2:3]
	v_cndmask_b32_e64 v51, 0, 1, s[24:25]
	v_cmp_ne_u32_e64 s[48:49], 1, v51
	s_andn2_b64 vcc, exec, s[24:25]
	v_mov_b32_e32 v51, 0
	v_mov_b64_e32 v[52:53], 0
	v_mov_b64_e32 v[54:55], 0
	v_mov_b64_e32 v[56:57], 0
	v_mov_b64_e32 v[58:59], 0
	v_mov_b64_e32 v[60:61], 0
	v_mov_b64_e32 v[62:63], 0
	v_mov_b64_e32 v[64:65], 0
	s_mov_b32 s78, s58
	s_mov_b32 s91, s59
	s_cbranch_vccnz .LBB0_184
	ds_read_b128 v[208:211], v189 offset:32768
	v_lshl_add_u32 v240, v190, 4, v175
	ds_read_b128 v[212:215], v240 offset:32768
	v_lshl_add_u32 v240, v188, 4, v175
	ds_read_b128 v[216:219], v240 offset:32768
	v_lshl_add_u32 v240, v187, 4, v175
	ds_read_b128 v[220:223], v240 offset:32768
	v_lshl_add_u32 v240, v186, 4, v175
	ds_read_b128 v[224:227], v240 offset:32768
	v_lshl_add_u32 v240, v185, 4, v175
	ds_read_b128 v[228:231], v240 offset:32768
	v_lshl_add_u32 v240, v177, 4, v175
	ds_read_b128 v[232:235], v240 offset:32768
	v_lshl_add_u32 v240, v176, 4, v175
	ds_read_b128 v[236:239], v240 offset:32768
	s_waitcnt lgkmcnt(7)
	v_mfma_f32_32x32x16_bf16 v[50:65], v[208:211], v[158:161], 0
	s_waitcnt lgkmcnt(6)
	v_mfma_f32_32x32x16_bf16 v[50:65], v[212:215], v[154:157], v[50:65]
	s_waitcnt lgkmcnt(5)
	v_mfma_f32_32x32x16_bf16 v[50:65], v[216:219], v[150:153], v[50:65]
	s_waitcnt lgkmcnt(4)
	v_mfma_f32_32x32x16_bf16 v[50:65], v[220:223], v[146:149], v[50:65]
	s_waitcnt lgkmcnt(3)
	v_mfma_f32_32x32x16_bf16 v[50:65], v[224:227], v[142:145], v[50:65]
	s_waitcnt lgkmcnt(2)
	v_mfma_f32_32x32x16_bf16 v[50:65], v[228:231], v[138:141], v[50:65]
	s_waitcnt lgkmcnt(1)
	v_mfma_f32_32x32x16_bf16 v[50:65], v[232:235], v[134:137], v[50:65]
	s_waitcnt lgkmcnt(0)
	v_mfma_f32_32x32x16_bf16 v[50:65], v[236:239], v[130:133], v[50:65]
